# rwkv_prep: shift_mu fetched with one dwordx4 per thread instead of four dependent load/wait pairs (on top of the tight mid-chain scanner)
# baseline (speedup 1.0000x reference)
.LBB0_613:
	s_or_b64 exec, exec, s[6:7]
	v_lshlrev_b32_e32 v0, 2, v0
	global_load_dwordx4 v[86:89], v0, s[10:11]
	s_waitcnt vmcnt(1)
	v_lshlrev_b32_e32 v1, 16, v4
	v_lshlrev_b32_e32 v9, 16, v2
	v_sub_f32_e32 v1, v1, v9
	s_waitcnt vmcnt(0)
	v_fmac_f32_e32 v9, v86, v1
	s_and_saveexec_b64 s[6:7], s[4:5]
	s_cbranch_execz .LBB0_619
	v_cmp_nlt_f32_e64 s[34:35], |v9|, s63
	s_and_saveexec_b64 s[44:45], s[34:35]
	s_xor_b64 s[34:35], exec, s[44:45]
	s_cbranch_execz .LBB0_616
	v_add_f32_e64 v1, |v9|, |v9|
	v_mul_f32_e32 v10, 0x3fb8aa3b, v1
	v_rndne_f32_e32 v11, v10
	s_mov_b32 s0, 0x3fb8aa3b
	v_sub_f32_e32 v12, v10, v11
	v_fma_f32 v10, v1, s0, -v10
	v_fmac_f32_e32 v10, 0x32a5705f, v1
	v_add_f32_e32 v10, v12, v10
	v_cvt_i32_f32_e32 v11, v11
	v_exp_f32_e32 v10, v10
	s_mov_b32 s0, 0xc2ce8ed0
	v_cmp_ngt_f32_e32 vcc, s0, v1
	s_mov_b32 s0, 0x42b17218
	v_ldexp_f32 v10, v10, v11
	v_cndmask_b32_e32 v10, 0, v10, vcc
	v_cmp_nlt_f32_e32 vcc, s0, v1
	s_nop 1
	v_cndmask_b32_e32 v1, v244, v10, vcc
	v_add_f32_e32 v1, 1.0, v1
	v_rcp_f32_e32 v1, v1
	s_nop 0
	v_fma_f32 v1, v1, -2.0, 1.0

.LBB0_619:
	s_or_b64 exec, exec, s[6:7]
	v_mov_b32_e32 v1, v145
	v_lshl_add_u64 v[0:1], s[10:11], 0, v[0:1]
	v_and_b32_e32 v2, 0xffff0000, v2
	v_and_b32_e32 v4, 0xffff0000, v4
	v_sub_f32_e32 v4, v4, v2
	v_fmac_f32_e32 v2, v4, v87
	s_and_saveexec_b64 s[6:7], s[4:5]
	s_cbranch_execz .LBB0_625
	v_cmp_nlt_f32_e64 s[34:35], |v2|, s63
	s_and_saveexec_b64 s[44:45], s[34:35]
	s_xor_b64 s[34:35], exec, s[44:45]
	s_cbranch_execz .LBB0_622
	v_add_f32_e64 v4, |v2|, |v2|
	v_mul_f32_e32 v10, 0x3fb8aa3b, v4
	v_rndne_f32_e32 v11, v10
	s_mov_b32 s0, 0x3fb8aa3b
	v_sub_f32_e32 v12, v10, v11
	v_fma_f32 v10, v4, s0, -v10
	v_fmac_f32_e32 v10, 0x32a5705f, v4
	v_add_f32_e32 v10, v12, v10
	v_cvt_i32_f32_e32 v11, v11
	v_exp_f32_e32 v10, v10
	s_mov_b32 s0, 0xc2ce8ed0
	v_cmp_ngt_f32_e32 vcc, s0, v4
	s_mov_b32 s0, 0x42b17218
	v_ldexp_f32 v10, v10, v11
	v_cndmask_b32_e32 v10, 0, v10, vcc
	v_cmp_nlt_f32_e32 vcc, s0, v4
	s_nop 1
	v_cndmask_b32_e32 v4, v244, v10, vcc
	v_add_f32_e32 v4, 1.0, v4
	v_rcp_f32_e32 v4, v4
	s_nop 0
	v_fma_f32 v4, v4, -2.0, 1.0

.LBB0_625:
	s_or_b64 exec, exec, s[6:7]
	v_lshlrev_b32_e32 v4, 16, v3
	v_lshlrev_b32_e32 v10, 16, v5
	v_sub_f32_e32 v10, v10, v4
	v_fmac_f32_e32 v4, v10, v88
	s_and_saveexec_b64 s[6:7], s[4:5]
	s_cbranch_execz .LBB0_631
	v_cmp_nlt_f32_e64 s[34:35], |v4|, s63
	s_and_saveexec_b64 s[44:45], s[34:35]
	s_xor_b64 s[34:35], exec, s[44:45]
	s_cbranch_execz .LBB0_628
	v_add_f32_e64 v10, |v4|, |v4|
	v_mul_f32_e32 v11, 0x3fb8aa3b, v10
	v_rndne_f32_e32 v12, v11
	s_mov_b32 s0, 0x3fb8aa3b
	v_sub_f32_e32 v13, v11, v12
	v_fma_f32 v11, v10, s0, -v11
	v_fmac_f32_e32 v11, 0x32a5705f, v10
	v_add_f32_e32 v11, v13, v11
	v_cvt_i32_f32_e32 v12, v12
	v_exp_f32_e32 v11, v11
	s_mov_b32 s0, 0xc2ce8ed0
	v_cmp_ngt_f32_e32 vcc, s0, v10
	s_mov_b32 s0, 0x42b17218
	v_ldexp_f32 v11, v11, v12
	v_cndmask_b32_e32 v11, 0, v11, vcc
	v_cmp_nlt_f32_e32 vcc, s0, v10
	s_nop 1
	v_cndmask_b32_e32 v10, v244, v11, vcc
	v_add_f32_e32 v10, 1.0, v10
	v_rcp_f32_e32 v10, v10
	s_nop 0
	v_fma_f32 v10, v10, -2.0, 1.0

.LBB0_631:
	s_or_b64 exec, exec, s[6:7]
	v_and_b32_e32 v3, 0xffff0000, v3
	v_and_b32_e32 v5, 0xffff0000, v5
	v_sub_f32_e32 v5, v5, v3
	v_fmac_f32_e32 v3, v5, v89
	s_and_saveexec_b64 s[6:7], s[4:5]
	s_cbranch_execz .LBB0_637
	v_cmp_nlt_f32_e64 s[34:35], |v3|, s63
	s_and_saveexec_b64 s[44:45], s[34:35]
	s_xor_b64 s[34:35], exec, s[44:45]
	s_cbranch_execz .LBB0_634
	v_add_f32_e64 v5, |v3|, |v3|
	v_mul_f32_e32 v10, 0x3fb8aa3b, v5
	v_rndne_f32_e32 v11, v10
	s_mov_b32 s0, 0x3fb8aa3b
	v_sub_f32_e32 v12, v10, v11
	v_fma_f32 v10, v5, s0, -v10
	v_fmac_f32_e32 v10, 0x32a5705f, v5
	v_add_f32_e32 v10, v12, v10
	v_cvt_i32_f32_e32 v11, v11
	v_exp_f32_e32 v10, v10
	s_mov_b32 s0, 0xc2ce8ed0
	v_cmp_ngt_f32_e32 vcc, s0, v5
	s_mov_b32 s0, 0x42b17218
	v_ldexp_f32 v10, v10, v11
	v_cndmask_b32_e32 v10, 0, v10, vcc
	v_cmp_nlt_f32_e32 vcc, s0, v5
	s_nop 1
	v_cndmask_b32_e32 v5, v244, v10, vcc
	v_add_f32_e32 v5, 1.0, v5
	v_rcp_f32_e32 v5, v5
	s_nop 0
	v_fma_f32 v5, v5, -2.0, 1.0

.LBB0_639:
	s_or_b64 exec, exec, s[6:7]
	global_load_dwordx4 v[86:89], v[0:1], off
	s_waitcnt vmcnt(1)
	v_lshlrev_b32_e32 v9, 16, v4
	v_lshlrev_b32_e32 v6, 16, v2
	v_sub_f32_e32 v9, v9, v6
	s_waitcnt vmcnt(0)
	v_fmac_f32_e32 v6, v86, v9
	s_and_saveexec_b64 s[6:7], s[4:5]
	s_cbranch_execz .LBB0_645
	v_cmp_nlt_f32_e64 s[34:35], |v6|, s63
	s_and_saveexec_b64 s[44:45], s[34:35]
	s_xor_b64 s[34:35], exec, s[44:45]
	s_cbranch_execz .LBB0_642
	v_add_f32_e64 v9, |v6|, |v6|
	v_mul_f32_e32 v10, 0x3fb8aa3b, v9
	v_rndne_f32_e32 v11, v10
	s_mov_b32 s0, 0x3fb8aa3b
	v_sub_f32_e32 v12, v10, v11
	v_fma_f32 v10, v9, s0, -v10
	v_fmac_f32_e32 v10, 0x32a5705f, v9
	v_add_f32_e32 v10, v12, v10
	v_cvt_i32_f32_e32 v11, v11
	v_exp_f32_e32 v10, v10
	s_mov_b32 s0, 0xc2ce8ed0
	v_cmp_ngt_f32_e32 vcc, s0, v9
	s_mov_b32 s0, 0x42b17218
	v_ldexp_f32 v10, v10, v11
	v_cndmask_b32_e32 v10, 0, v10, vcc
	v_cmp_nlt_f32_e32 vcc, s0, v9
	s_nop 1
	v_cndmask_b32_e32 v9, v244, v10, vcc
	v_add_f32_e32 v9, 1.0, v9
	v_rcp_f32_e32 v9, v9
	s_nop 0
	v_fma_f32 v9, v9, -2.0, 1.0

.LBB0_645:
	s_or_b64 exec, exec, s[6:7]
	v_and_b32_e32 v2, 0xffff0000, v2
	v_and_b32_e32 v4, 0xffff0000, v4
	v_sub_f32_e32 v4, v4, v2
	v_fmac_f32_e32 v2, v4, v87
	s_and_saveexec_b64 s[6:7], s[4:5]
	s_cbranch_execz .LBB0_651
	v_cmp_nlt_f32_e64 s[34:35], |v2|, s63
	s_and_saveexec_b64 s[44:45], s[34:35]
	s_xor_b64 s[34:35], exec, s[44:45]
	s_cbranch_execz .LBB0_648
	v_add_f32_e64 v4, |v2|, |v2|
	v_mul_f32_e32 v9, 0x3fb8aa3b, v4
	v_rndne_f32_e32 v10, v9
	s_mov_b32 s0, 0x3fb8aa3b
	v_sub_f32_e32 v11, v9, v10
	v_fma_f32 v9, v4, s0, -v9
	v_fmac_f32_e32 v9, 0x32a5705f, v4
	v_add_f32_e32 v9, v11, v9
	v_cvt_i32_f32_e32 v10, v10
	v_exp_f32_e32 v9, v9
	s_mov_b32 s0, 0xc2ce8ed0
	v_cmp_ngt_f32_e32 vcc, s0, v4
	s_mov_b32 s0, 0x42b17218
	v_ldexp_f32 v9, v9, v10
	v_cndmask_b32_e32 v9, 0, v9, vcc
	v_cmp_nlt_f32_e32 vcc, s0, v4
	s_nop 1
	v_cndmask_b32_e32 v4, v244, v9, vcc
	v_add_f32_e32 v4, 1.0, v4
	v_rcp_f32_e32 v4, v4
	s_nop 0
	v_fma_f32 v4, v4, -2.0, 1.0

.LBB0_651:
	s_or_b64 exec, exec, s[6:7]
	v_lshlrev_b32_e32 v4, 16, v3
	v_lshlrev_b32_e32 v9, 16, v5
	v_sub_f32_e32 v9, v9, v4
	v_fmac_f32_e32 v4, v9, v88
	s_and_saveexec_b64 s[6:7], s[4:5]
	s_cbranch_execz .LBB0_657
	v_cmp_nlt_f32_e64 s[34:35], |v4|, s63
	s_and_saveexec_b64 s[44:45], s[34:35]
	s_xor_b64 s[34:35], exec, s[44:45]
	s_cbranch_execz .LBB0_654
	v_add_f32_e64 v9, |v4|, |v4|
	v_mul_f32_e32 v10, 0x3fb8aa3b, v9
	v_rndne_f32_e32 v11, v10
	s_mov_b32 s0, 0x3fb8aa3b
	v_sub_f32_e32 v12, v10, v11
	v_fma_f32 v10, v9, s0, -v10
	v_fmac_f32_e32 v10, 0x32a5705f, v9
	v_add_f32_e32 v10, v12, v10
	v_cvt_i32_f32_e32 v11, v11
	v_exp_f32_e32 v10, v10
	s_mov_b32 s0, 0xc2ce8ed0
	v_cmp_ngt_f32_e32 vcc, s0, v9
	s_mov_b32 s0, 0x42b17218
	v_ldexp_f32 v10, v10, v11
	v_cndmask_b32_e32 v10, 0, v10, vcc
	v_cmp_nlt_f32_e32 vcc, s0, v9
	s_nop 1
	v_cndmask_b32_e32 v9, v244, v10, vcc
	v_add_f32_e32 v9, 1.0, v9
	v_rcp_f32_e32 v9, v9
	s_nop 0
	v_fma_f32 v9, v9, -2.0, 1.0

.LBB0_657:
	s_or_b64 exec, exec, s[6:7]
	v_and_b32_e32 v0, 0xffff0000, v3
	v_and_b32_e32 v3, 0xffff0000, v5
	v_sub_f32_e32 v3, v3, v0
	v_fmac_f32_e32 v0, v3, v89
	s_and_saveexec_b64 s[6:7], s[4:5]
	s_cbranch_execz .LBB0_663
	v_cmp_nlt_f32_e64 s[34:35], |v0|, s63
	s_and_saveexec_b64 s[44:45], s[34:35]
	s_xor_b64 s[34:35], exec, s[44:45]
	s_cbranch_execz .LBB0_660
	v_add_f32_e64 v1, |v0|, |v0|
	v_mul_f32_e32 v3, 0x3fb8aa3b, v1
	v_rndne_f32_e32 v5, v3
	s_mov_b32 s0, 0x3fb8aa3b
	v_sub_f32_e32 v9, v3, v5
	v_fma_f32 v3, v1, s0, -v3
	v_fmac_f32_e32 v3, 0x32a5705f, v1
	v_add_f32_e32 v3, v9, v3
	v_cvt_i32_f32_e32 v5, v5
	v_exp_f32_e32 v3, v3
	s_mov_b32 s0, 0xc2ce8ed0
	v_cmp_ngt_f32_e32 vcc, s0, v1
	s_mov_b32 s0, 0x42b17218
	v_ldexp_f32 v3, v3, v5
	v_cndmask_b32_e32 v3, 0, v3, vcc
	v_cmp_nlt_f32_e32 vcc, s0, v1
	s_nop 1
	v_cndmask_b32_e32 v1, v244, v3, vcc
	v_add_f32_e32 v1, 1.0, v1
	v_rcp_f32_e32 v1, v1
	s_nop 0
	v_fma_f32 v1, v1, -2.0, 1.0
